# attention loop: QK MFMAs hoisted to head of step, no-op lgkmcnt waits removed, waits thinned, static setprio 1 for waves 4-7
# baseline (speedup 1.0000x reference)
; #define WAIT_BAR(N) asm volatile("s_waitcnt vmcnt(" #N ") lgkmcnt(0)\n\ts_barrier":::"memory")
;   #define DMA_K(t,slot) glds16(ksrc+(long)(t)*KVBLK*DM,(unsigned)__builtin_amdgcn_readfirstlane(kdst+(slot)))
;   #define DMA_V(t,slot) do{ glds16(vsrc+(long)(t)*KVBLK*DM,(unsigned)__builtin_amdgcn_readfirstlane(vdst+2*(slot))); glds16(vsrc+(long)(t)*KVBLK*DM+64,(unsigned)__builtin_amdgcn_readfirstlane(vdst+2*(slot)+8192)); }while(0)
;   #define CMASK(P0,P1,t) do{int jb_=(t)-(NT-4); if(jb_>=0)cmask(P0,P1,jb_,qrel,hi);}while(0)
;   #define ROT() do{sl_prev=sl_cur;sl_cur=sl_next;sl_next=(sl_next==(NSLOT-1)*SLOTB)?0:sl_next+SLOTB;}while(0)
;   #define CMASK(P0,P1,t) do{}while(0)
;   #define CMASK(P0,P1,t) do{int jb_=(t)-(NT-4); if(jb_>=0)cmask(P0,P1,jb_,qrel,hi);}while(0)
; template<int DUMMY> __device__ __forceinline__ void attn_pass2(const bf16*Qh,const bf16*__restrict__ Kh,const bf16*__restrict__ Vh,const int q0,char*shm,f32x16 (&o)[4]){
;     ...
;   float l_reg=0.f;o[0]=f32x16{};o[1]=f32x16{};o[2]=f32x16{};o[3]=f32x16{};
;   const f32x16 zero16=f32x16{};
;   const int qrel=wid*QBLK+r32;
;     ...
;   f32x16 pA0,pA1,pB0,pB1;
;   int sl_prev=0,sl_cur=0,sl_next=SLOTB;
;     ...
;   DMA_K(2,2*SLOTB);
;   WAIT_BAR(4);
;   qkt(pA0,pA1,Kbase,qr,zero16,r32,hi);CMASK(pA0,pA1,0);
;   _Pragma("unroll") for(int r=0;r<16;++r){pA0[r]=__builtin_amdgcn_exp2f(pA0[r]);pA1[r]=__builtin_amdgcn_exp2f(pA1[r]);}
;   WAIT_BAR(0);
;   DMA_K(3,0);DMA_V(1,SLOTB);
;   ROT();
;   kload8(kf,kp0+sl_cur);
;   WAIT_BAR(3);
;   s16x4 vlo[8],vhi[8]; u32x4 pw0,pw1,pw2,pw3;
.LBB0_302:
	s_waitcnt vmcnt(0) lgkmcnt(0)
	s_barrier
	s_ashr_i32 s25, s14, 6
	s_nop 7
	v_exp_f32_e32 v96, v0
	v_exp_f32_e32 v97, v1
	v_lshl_add_u64 v[0:1], v[208:209], 0, s[42:43]
	s_mov_b32 s14, m0
	s_mov_b32 m0, s20
	s_nop 0
	global_load_lds_dwordx4 v[0:1], off
	s_mov_b32 m0, s14
	s_mov_b64 s[14:15], 0x60000
	s_cmp_lg_u32 0, -1
	v_lshl_add_u64 v[0:1], v[32:33], 0, s[14:15]
	s_cselect_b32 s14, 0, 0
	s_add_i32 s11, s14, s11
	s_add_i32 s14, s11, 0xa000
	s_mov_b32 s15, m0
	s_mov_b32 m0, s14
	s_nop 0
	global_load_lds_dwordx4 v[0:1], off
	s_mov_b32 m0, s15
	s_mov_b64 s[14:15], 0x60080
	v_lshl_add_u64 v[0:1], v[32:33], 0, s[14:15]
	s_add_i32 s11, s11, 0xc000
	s_mov_b32 s14, m0
	s_mov_b32 m0, s11
	s_nop 0
	global_load_lds_dwordx4 v[0:1], off
	s_mov_b32 m0, s14
	ds_read_b128 v[204:207], v241 offset:8192
	ds_read_b128 v[200:203], v241 offset:8704
	ds_read_b128 v[196:199], v241 offset:10240
	ds_read_b128 v[192:195], v241 offset:10752
	ds_read_b128 v[188:191], v241 offset:12288
	ds_read_b128 v[184:187], v241 offset:12800
	ds_read_b128 v[180:183], v241 offset:14336
	ds_read_b128 v[176:179], v241 offset:14848
	v_lshlrev_b32_e32 v36, 1, v34
	v_exp_f32_e32 v80, v16
	v_exp_f32_e32 v81, v17
	v_exp_f32_e32 v98, v2
	v_exp_f32_e32 v82, v18
	v_exp_f32_e32 v99, v3
	v_exp_f32_e32 v83, v19
	v_exp_f32_e32 v100, v4
	v_exp_f32_e32 v84, v20
	v_exp_f32_e32 v101, v5
	v_exp_f32_e32 v85, v21
	v_exp_f32_e32 v102, v6
	v_exp_f32_e32 v86, v22
	v_exp_f32_e32 v103, v7
	v_exp_f32_e32 v87, v23
	v_exp_f32_e32 v104, v8
	v_exp_f32_e32 v88, v24
	v_exp_f32_e32 v105, v9
	v_exp_f32_e32 v89, v25
	v_exp_f32_e32 v106, v10
	v_exp_f32_e32 v90, v26
	v_exp_f32_e32 v107, v11
	v_exp_f32_e32 v91, v27
	v_exp_f32_e32 v108, v12
	v_exp_f32_e32 v92, v28
	v_exp_f32_e32 v109, v13
	v_exp_f32_e32 v93, v29
	v_exp_f32_e32 v110, v14
	v_exp_f32_e32 v94, v30
	v_exp_f32_e32 v111, v15
	v_exp_f32_e32 v95, v31
	v_and_b32_e32 v36, 32, v36
	v_lshlrev_b32_e32 v37, 4, v34
	s_waitcnt vmcnt(3) lgkmcnt(0)
	s_barrier
	v_add3_u32 v35, 0, v36, v35
	v_lshlrev_b32_e32 v36, 8, v214
	v_and_b32_e32 v37, 0xc0, v37
	v_and_b32_e32 v0, 3, v34
	s_mov_b32 s35, 1
	v_add3_u32 v239, v35, v36, v37
	s_mov_b32 s37, 0
	s_mov_b32 s15, 0
	s_cmp_lt_i32 s2, 1
	v_lshlrev_b32_e32 v210, 4, v0
	s_cbranch_scc1 .LBB0_314
	s_add_i32 s11, s25, -5
	s_lshl_b64 s[26:27], s[54:55], 1
	s_add_u32 s14, s12, s26
	s_addc_u32 s24, s13, s27
	s_add_u32 s26, s14, s31
	v_mov_b32_e32 v211, v213
	s_addc_u32 s27, s24, s29
	v_lshl_add_u64 v[0:1], s[26:27], 0, v[210:211]
	v_lshl_add_u64 v[0:1], v[0:1], 0, v[212:213]
	v_mov_b32_e32 v64, 0
	v_lshl_add_u64 v[66:67], s[6:7], 0, v[0:1]
	s_movk_i32 s28, 0x4000
	s_movk_i32 s27, 0x2000
	s_mov_b64 s[56:57], 0
	v_mov_b32_e32 v0, 0
	v_mov_b32_e32 v1, v64
	v_mov_b32_e32 v2, v64
	v_mov_b32_e32 v3, v64
	v_mov_b32_e32 v4, v64
	v_mov_b32_e32 v5, v64
	v_mov_b32_e32 v6, v64
	v_mov_b32_e32 v7, v64
	v_mov_b32_e32 v8, v64
	v_mov_b32_e32 v9, v64
	v_mov_b32_e32 v10, v64
	v_mov_b32_e32 v11, v64
	v_mov_b32_e32 v12, v64
	v_mov_b32_e32 v13, v64
	v_mov_b32_e32 v14, v64
	v_mov_b32_e32 v15, v64
	v_mov_b32_e32 v16, 0
	v_mov_b32_e32 v17, v64
	v_mov_b32_e32 v18, v64
	v_mov_b32_e32 v19, v64
	v_mov_b32_e32 v20, v64
	v_mov_b32_e32 v21, v64
	v_mov_b32_e32 v22, v64
	v_mov_b32_e32 v23, v64
	v_mov_b32_e32 v24, v64
	v_mov_b32_e32 v25, v64
	v_mov_b32_e32 v26, v64
	v_mov_b32_e32 v27, v64
	v_mov_b32_e32 v28, v64
	v_mov_b32_e32 v29, v64
	v_mov_b32_e32 v30, v64
	v_mov_b32_e32 v31, v64
	v_mov_b32_e32 v32, 0
	v_mov_b32_e32 v33, v64
	v_mov_b32_e32 v34, v64
	v_mov_b32_e32 v35, v64
	v_mov_b32_e32 v36, v64
	v_mov_b32_e32 v37, v64
	v_mov_b32_e32 v38, v64
	v_mov_b32_e32 v39, v64
	v_mov_b32_e32 v40, v64
	v_mov_b32_e32 v41, v64
	v_mov_b32_e32 v42, v64
	v_mov_b32_e32 v43, v64
	v_mov_b32_e32 v44, v64
	v_mov_b32_e32 v45, v64
	v_mov_b32_e32 v46, v64
	v_mov_b32_e32 v47, v64
	v_mov_b32_e32 v48, 0
	v_mov_b32_e32 v49, v64
	v_mov_b32_e32 v50, v64
	v_mov_b32_e32 v51, v64
	v_mov_b32_e32 v52, v64
	v_mov_b32_e32 v53, v64
	v_mov_b32_e32 v54, v64
	v_mov_b32_e32 v55, v64
	v_mov_b32_e32 v56, v64
	v_mov_b32_e32 v57, v64
	v_mov_b32_e32 v58, v64
	v_mov_b32_e32 v59, v64
	v_mov_b32_e32 v60, v64
	v_mov_b32_e32 v61, v64
	v_mov_b32_e32 v62, v64
	v_mov_b32_e32 v63, v64
	s_cmp_lt_u32 s18, 0x100
	s_cbranch_scc1 .Lattn_prio_skip
	s_setprio 1
.Lattn_prio_skip:
.LBB0_304:
	s_mov_b32 s37, s28
	s_mov_b32 s14, s27
	v_mfma_f32_32x32x16_bf16 v[128:143], v[204:207], v[168:171], 0
	v_mfma_f32_32x32x16_bf16 v[112:127], v[200:203], v[168:171], 0
	v_lshl_add_u32 v65, s15, 1, v239
	ds_read_b64_tr_b16 v[72:73], v65 offset:24576
	ds_read_b64_tr_b16 v[74:75], v65 offset:25088
	v_add_f32_e32 v68, v96, v97
	v_add_f32_e32 v68, v98, v68
	v_add_f32_e32 v68, v99, v68
	v_add_f32_e32 v68, v100, v68
	v_add_f32_e32 v68, v101, v68
	v_cvt_pk_bf16_f32 v172, v96, v97
	v_cvt_pk_bf16_f32 v173, v98, v99
	ds_read_b64_tr_b16 v[76:77], v65 offset:28672
	ds_read_b64_tr_b16 v[78:79], v65 offset:29184
	v_add_f32_e32 v68, v102, v68
	v_add_f32_e32 v68, v103, v68
	v_add_f32_e32 v68, v104, v68
	v_add_f32_e32 v68, v105, v68
	v_cvt_pk_bf16_f32 v174, v100, v101
	v_cvt_pk_bf16_f32 v175, v102, v103
	ds_read_b64_tr_b16 v[96:97], v65 offset:32768
	ds_read_b64_tr_b16 v[98:99], v65 offset:33280
	v_add_f32_e32 v68, v106, v68
	v_add_f32_e32 v68, v107, v68
	v_add_f32_e32 v68, v108, v68
	v_add_f32_e32 v68, v109, v68
	v_cvt_pk_bf16_f32 v164, v104, v105
	v_cvt_pk_bf16_f32 v165, v106, v107
	v_mfma_f32_32x32x16_bf16 v[128:143], v[196:199], v[160:163], v[128:143]
	ds_read_b64_tr_b16 v[100:101], v65 offset:36864
	ds_read_b64_tr_b16 v[102:103], v65 offset:37376
	v_add_f32_e32 v68, v110, v68
	v_add_f32_e32 v68, v111, v68
	v_add_f32_e32 v68, v80, v68
	v_add_f32_e32 v68, v81, v68
	v_cvt_pk_bf16_f32 v166, v108, v109
	v_cvt_pk_bf16_f32 v167, v110, v111
	v_mfma_f32_32x32x16_bf16 v[112:127], v[192:195], v[160:163], v[112:127]
	ds_read_b64_tr_b16 v[104:105], v65 offset:25600
	ds_read_b64_tr_b16 v[106:107], v65 offset:26112
	v_add_f32_e32 v68, v82, v68
	v_add_f32_e32 v68, v83, v68
	v_add_f32_e32 v68, v84, v68
	v_add_f32_e32 v68, v85, v68
	v_cvt_pk_bf16_f32 v156, v80, v81
	v_cvt_pk_bf16_f32 v157, v82, v83
	v_mfma_f32_32x32x16_bf16 v[128:143], v[188:191], v[152:155], v[128:143]
	ds_read_b64_tr_b16 v[80:81], v65 offset:29696
	ds_read_b64_tr_b16 v[82:83], v65 offset:30208
	v_add_f32_e32 v68, v86, v68
	v_add_f32_e32 v68, v87, v68
	v_add_f32_e32 v68, v88, v68
	v_add_f32_e32 v68, v89, v68
	v_cvt_pk_bf16_f32 v158, v84, v85
	v_cvt_pk_bf16_f32 v159, v86, v87
	v_mfma_f32_32x32x16_bf16 v[112:127], v[184:187], v[152:155], v[112:127]
	ds_read_b64_tr_b16 v[84:85], v65 offset:33792
	ds_read_b64_tr_b16 v[86:87], v65 offset:34304
	v_add_f32_e32 v68, v90, v68
	v_add_f32_e32 v68, v91, v68
	v_add_f32_e32 v68, v92, v68
	v_add_f32_e32 v68, v93, v68
	v_cvt_pk_bf16_f32 v148, v88, v89
	v_cvt_pk_bf16_f32 v149, v90, v91
	v_mfma_f32_32x32x16_bf16 v[128:143], v[180:183], v[144:147], v[128:143]
	ds_read_b64_tr_b16 v[88:89], v65 offset:37888
	ds_read_b64_tr_b16 v[90:91], v65 offset:38400
	v_add_f32_e32 v68, v94, v68
	v_add_f32_e32 v68, v95, v68
	v_add_f32_e32 v68, 0, v68
	v_cvt_pk_bf16_f32 v150, v92, v93
	v_cvt_pk_bf16_f32 v151, v94, v95
	v_mfma_f32_32x32x16_bf16 v[112:127], v[176:179], v[144:147], v[112:127]
	v_lshl_add_u64 v[70:71], v[208:209], 0, s[56:57]
	v_add_f32_e32 v64, v64, v68
	v_lshl_add_u64 v[244:245], v[70:71], 0, s[44:45]
	v_lshl_add_u64 v[68:69], v[66:67], 0, s[56:57]
	v_lshl_add_u64 v[246:247], v[68:69], 0, s[46:47]
	v_lshl_add_u64 v[248:249], v[68:69], 0, s[48:49]
	s_waitcnt lgkmcnt(12)
	v_mfma_f32_32x32x16_bf16 v[48:63], v[172:175], v[72:75], v[48:63]
	v_exp_f32_e32 v128, v128
	v_exp_f32_e32 v129, v129
	ds_read_b64_tr_b16 v[72:73], v65 offset:26624
	ds_read_b64_tr_b16 v[74:75], v65 offset:27136
	v_mfma_f32_32x32x16_bf16 v[32:47], v[172:175], v[76:79], v[32:47]
	v_exp_f32_e32 v130, v130
	v_exp_f32_e32 v131, v131
	ds_read_b64_tr_b16 v[76:77], v65 offset:30720
	ds_read_b64_tr_b16 v[78:79], v65 offset:31232
	s_add_i32 s15, s27, s20
	s_mov_b32 m0, s15
	s_nop 0
	global_load_lds_dwordx4 v[244:245], off
	s_waitcnt lgkmcnt(12)
	v_mfma_f32_32x32x16_bf16 v[16:31], v[172:175], v[96:99], v[16:31]
	v_exp_f32_e32 v132, v132
	v_exp_f32_e32 v133, v133
	ds_read_b64_tr_b16 v[92:93], v65 offset:34816
	ds_read_b64_tr_b16 v[94:95], v65 offset:35328
	v_mfma_f32_32x32x16_bf16 v[0:15], v[172:175], v[100:103], v[0:15]
	v_exp_f32_e32 v134, v134
	v_exp_f32_e32 v135, v135
	ds_read_b64_tr_b16 v[96:97], v65 offset:38912
	ds_read_b64_tr_b16 v[98:99], v65 offset:39424
	s_waitcnt lgkmcnt(12)
	v_mfma_f32_32x32x16_bf16 v[48:63], v[164:167], v[104:107], v[48:63]
	v_exp_f32_e32 v136, v136
	v_exp_f32_e32 v137, v137
	ds_read_b64_tr_b16 v[100:101], v65 offset:27648
	ds_read_b64_tr_b16 v[102:103], v65 offset:28160
	s_lshl_b32 s15, s28, 1
	s_add_i32 s15, s15, s21
	s_mov_b32 m0, s15
	s_nop 0
	global_load_lds_dwordx4 v[246:247], off
	v_mfma_f32_32x32x16_bf16 v[32:47], v[164:167], v[80:83], v[32:47]
	v_exp_f32_e32 v138, v138
	v_exp_f32_e32 v139, v139
	ds_read_b64_tr_b16 v[80:81], v65 offset:31744
	ds_read_b64_tr_b16 v[82:83], v65 offset:32256
	s_waitcnt lgkmcnt(12)
	v_mfma_f32_32x32x16_bf16 v[16:31], v[164:167], v[84:87], v[16:31]
	v_exp_f32_e32 v140, v140
	v_exp_f32_e32 v141, v141
	ds_read_b64_tr_b16 v[84:85], v65 offset:35840
	ds_read_b64_tr_b16 v[86:87], v65 offset:36352
	v_mfma_f32_32x32x16_bf16 v[0:15], v[164:167], v[88:91], v[0:15]
	v_exp_f32_e32 v142, v142
	v_exp_f32_e32 v143, v143
	ds_read_b64_tr_b16 v[88:89], v65 offset:39936
	ds_read_b64_tr_b16 v[90:91], v65 offset:40448
	s_lshl_b32 s15, s28, 1
	s_add_i32 s15, s15, s21
	s_addk_i32 s15, 0x2000
	s_mov_b32 m0, s15
	s_nop 0
	global_load_lds_dwordx4 v[248:249], off
	s_waitcnt lgkmcnt(14)
	v_mfma_f32_32x32x16_bf16 v[48:63], v[156:159], v[72:75], v[48:63]
	v_exp_f32_e32 v112, v112
	v_exp_f32_e32 v113, v113
	s_waitcnt lgkmcnt(12)
	v_mfma_f32_32x32x16_bf16 v[32:47], v[156:159], v[76:79], v[32:47]
	v_exp_f32_e32 v114, v114
	v_exp_f32_e32 v115, v115
	v_add_u32_e32 v65, s37, v241
	ds_read_b128 v[72:75], v65
	ds_read_b128 v[76:79], v65 offset:512
	s_waitcnt lgkmcnt(12)
	v_mfma_f32_32x32x16_bf16 v[16:31], v[156:159], v[92:95], v[16:31]
	v_exp_f32_e32 v116, v116
	v_exp_f32_e32 v117, v117
	ds_read_b128 v[176:179], v65 offset:2048
	ds_read_b128 v[180:183], v65 offset:2560
	s_waitcnt lgkmcnt(12)
	v_mfma_f32_32x32x16_bf16 v[0:15], v[156:159], v[96:99], v[0:15]
	v_exp_f32_e32 v118, v118
	v_exp_f32_e32 v119, v119
	ds_read_b128 v[184:187], v65 offset:4096
	ds_read_b128 v[188:191], v65 offset:4608
	s_waitcnt lgkmcnt(12)
	v_mfma_f32_32x32x16_bf16 v[48:63], v[148:151], v[100:103], v[48:63]
	v_exp_f32_e32 v120, v120
	v_exp_f32_e32 v121, v121
	ds_read_b128 v[192:195], v65 offset:6144
	ds_read_b128 v[196:199], v65 offset:6656
	s_waitcnt lgkmcnt(12)
	v_mfma_f32_32x32x16_bf16 v[32:47], v[148:151], v[80:83], v[32:47]
	v_exp_f32_e32 v122, v122
	v_exp_f32_e32 v123, v123
	s_waitcnt lgkmcnt(10)
	v_mfma_f32_32x32x16_bf16 v[16:31], v[148:151], v[84:87], v[16:31]
	v_exp_f32_e32 v124, v124
	v_exp_f32_e32 v125, v125
	s_waitcnt lgkmcnt(8)
	v_mfma_f32_32x32x16_bf16 v[0:15], v[148:151], v[88:91], v[0:15]
	v_exp_f32_e32 v126, v126
	v_exp_f32_e32 v127, v127
	s_waitcnt vmcnt(3) lgkmcnt(0)
	s_barrier
; #define WAIT_BAR(N) asm volatile("s_waitcnt vmcnt(" #N ") lgkmcnt(0)\n\ts_barrier":::"memory")
;   #define ROT() do{sl_prev=sl_cur;sl_cur=sl_next;sl_next=(sl_next==(NSLOT-1)*SLOTB)?0:sl_next+SLOTB;}while(0)
; template<int DUMMY> __device__ __forceinline__ void attn_pass2(const bf16*Qh,const bf16*__restrict__ Kh,const bf16*__restrict__ Vh,const int q0,char*shm,f32x16 (&o)[4]){
;     ...
;     STEP(pB0,pB1,pA0,pA1,t,true,true,true);     WAIT_BAR(3); ROT();
;     STEP(pA0,pA1,pB0,pB1,t+1,true,true,true);   WAIT_BAR(3); ROT();
	v_mfma_f32_32x32x16_bf16 v[96:111], v[72:75], v[168:171], 0
	v_mfma_f32_32x32x16_bf16 v[80:95], v[76:79], v[168:171], 0
	s_add_i32 s15, s28, 0x2000
	s_cmpk_lg_i32 s28, 0x4000
	s_cselect_b32 s27, s15, 0
	v_lshl_add_u32 v65, s14, 1, v239
	ds_read_b64_tr_b16 v[200:201], v65 offset:24576
	ds_read_b64_tr_b16 v[202:203], v65 offset:25088
	v_add_f32_e32 v243, v128, v129
	v_add_f32_e32 v243, v130, v243
	v_add_f32_e32 v243, v131, v243
	v_add_f32_e32 v243, v132, v243
	v_add_f32_e32 v243, v133, v243
	v_cvt_pk_bf16_f32 v172, v128, v129
	v_cvt_pk_bf16_f32 v173, v130, v131
	ds_read_b64_tr_b16 v[72:73], v65 offset:28672
	ds_read_b64_tr_b16 v[74:75], v65 offset:29184
	v_add_f32_e32 v243, v134, v243
	v_add_f32_e32 v243, v135, v243
	v_add_f32_e32 v243, v136, v243
	v_add_f32_e32 v128, v137, v243
	v_cvt_pk_bf16_f32 v174, v132, v133
	v_cvt_pk_bf16_f32 v175, v134, v135
	ds_read_b64_tr_b16 v[76:77], v65 offset:32768
	ds_read_b64_tr_b16 v[78:79], v65 offset:33280
	v_mfma_f32_32x32x16_bf16 v[96:111], v[176:179], v[160:163], v[96:111]
	v_add_f32_e32 v128, v138, v128
	v_add_f32_e32 v128, v139, v128
	v_add_f32_e32 v128, v140, v128
	v_add_f32_e32 v132, v141, v128
	v_cvt_pk_bf16_f32 v164, v136, v137
	v_cvt_pk_bf16_f32 v165, v138, v139
	ds_read_b64_tr_b16 v[128:129], v65 offset:36864
	ds_read_b64_tr_b16 v[130:131], v65 offset:37376
	v_mfma_f32_32x32x16_bf16 v[80:95], v[180:183], v[160:163], v[80:95]
	v_add_f32_e32 v132, v142, v132
	v_add_f32_e32 v132, v143, v132
	v_add_f32_e32 v132, v112, v132
	v_add_f32_e32 v136, v113, v132
	v_cvt_pk_bf16_f32 v166, v140, v141
	v_cvt_pk_bf16_f32 v167, v142, v143
	ds_read_b64_tr_b16 v[132:133], v65 offset:25600
	ds_read_b64_tr_b16 v[134:135], v65 offset:26112
	v_mfma_f32_32x32x16_bf16 v[96:111], v[184:187], v[152:155], v[96:111]
	v_add_f32_e32 v136, v114, v136
	v_add_f32_e32 v136, v115, v136
	v_add_f32_e32 v136, v116, v136
	v_add_f32_e32 v136, v117, v136
	v_cvt_pk_bf16_f32 v156, v112, v113
	v_cvt_pk_bf16_f32 v157, v114, v115
	ds_read_b64_tr_b16 v[112:113], v65 offset:29696
	ds_read_b64_tr_b16 v[114:115], v65 offset:30208
	v_mfma_f32_32x32x16_bf16 v[80:95], v[188:191], v[152:155], v[80:95]
	v_add_f32_e32 v136, v118, v136
	v_add_f32_e32 v136, v119, v136
	v_add_f32_e32 v136, v120, v136
	v_add_f32_e32 v136, v121, v136
	v_cvt_pk_bf16_f32 v158, v116, v117
	v_cvt_pk_bf16_f32 v159, v118, v119
	ds_read_b64_tr_b16 v[116:117], v65 offset:33792
	ds_read_b64_tr_b16 v[118:119], v65 offset:34304
	v_mfma_f32_32x32x16_bf16 v[96:111], v[192:195], v[144:147], v[96:111]
	v_add_f32_e32 v136, v122, v136
	v_add_f32_e32 v136, v123, v136
	v_add_f32_e32 v136, v124, v136
	v_add_f32_e32 v136, v125, v136
	v_cvt_pk_bf16_f32 v148, v120, v121
	v_cvt_pk_bf16_f32 v149, v122, v123
	ds_read_b64_tr_b16 v[120:121], v65 offset:37888
	ds_read_b64_tr_b16 v[122:123], v65 offset:38400
	v_mfma_f32_32x32x16_bf16 v[80:95], v[196:199], v[144:147], v[80:95]
	v_add_f32_e32 v136, v126, v136
	v_add_f32_e32 v136, v127, v136
	v_add_f32_e32 v136, 0, v136
	v_cvt_pk_bf16_f32 v150, v124, v125
	v_cvt_pk_bf16_f32 v151, v126, v127
	s_mov_b64 s[14:15], 0x1e0000
	v_lshl_add_u64 v[244:245], v[70:71], 0, s[14:15]
	s_mov_b64 s[14:15], 0x10121000
	v_lshl_add_u64 v[246:247], v[68:69], 0, s[14:15]
	s_mov_b64 s[14:15], 0x10121080
	v_lshl_add_u64 v[248:249], v[68:69], 0, s[14:15]
	v_add_f32_e32 v64, v64, v136
	s_add_i32 s35, s35, 2
	s_waitcnt lgkmcnt(12)
	v_mfma_f32_32x32x16_bf16 v[48:63], v[172:175], v[200:203], v[48:63]
	v_exp_f32_e32 v96, v96
	v_exp_f32_e32 v97, v97
	ds_read_b64_tr_b16 v[68:69], v65 offset:26624
	ds_read_b64_tr_b16 v[70:71], v65 offset:27136
	v_mfma_f32_32x32x16_bf16 v[32:47], v[172:175], v[72:75], v[32:47]
	v_exp_f32_e32 v98, v98
	v_exp_f32_e32 v99, v99
	ds_read_b64_tr_b16 v[72:73], v65 offset:30720
	ds_read_b64_tr_b16 v[74:75], v65 offset:31232
	s_add_i32 s24, s28, s20
	s_mov_b32 m0, s24
	s_nop 0
	global_load_lds_dwordx4 v[244:245], off
	s_waitcnt lgkmcnt(12)
; #define WAIT_BAR(N) asm volatile("s_waitcnt vmcnt(" #N ") lgkmcnt(0)\n\ts_barrier":::"memory")
;   #define ROT() do{sl_prev=sl_cur;sl_cur=sl_next;sl_next=(sl_next==(NSLOT-1)*SLOTB)?0:sl_next+SLOTB;}while(0)
; template<int DUMMY> __device__ __forceinline__ void attn_pass2(const bf16*Qh,const bf16*__restrict__ Kh,const bf16*__restrict__ Vh,const int q0,char*shm,f32x16 (&o)[4]){
;     ...
;   int t=1;
;     ...
;   for(;t+5<NT;t+=2){
;     STEP(pB0,pB1,pA0,pA1,t,true,true,true);     WAIT_BAR(3); ROT();
;     STEP(pA0,pA1,pB0,pB1,t+1,true,true,true);   WAIT_BAR(3); ROT();
;   }
	v_mfma_f32_32x32x16_bf16 v[16:31], v[172:175], v[76:79], v[16:31]
	v_exp_f32_e32 v100, v100
	v_exp_f32_e32 v101, v101
	ds_read_b64_tr_b16 v[76:77], v65 offset:34816
	ds_read_b64_tr_b16 v[78:79], v65 offset:35328
	v_mfma_f32_32x32x16_bf16 v[0:15], v[172:175], v[128:131], v[0:15]
	v_exp_f32_e32 v102, v102
	v_exp_f32_e32 v103, v103
	ds_read_b64_tr_b16 v[124:125], v65 offset:38912
	ds_read_b64_tr_b16 v[126:127], v65 offset:39424
	s_waitcnt lgkmcnt(12)
	v_mfma_f32_32x32x16_bf16 v[48:63], v[164:167], v[132:135], v[48:63]
	v_exp_f32_e32 v104, v104
	v_exp_f32_e32 v105, v105
	ds_read_b64_tr_b16 v[128:129], v65 offset:27648
	ds_read_b64_tr_b16 v[130:131], v65 offset:28160
	s_lshl_b32 s24, s27, 1
	s_add_i32 s24, s24, s21
	s_mov_b32 m0, s24
	s_nop 0
	global_load_lds_dwordx4 v[246:247], off
	v_mfma_f32_32x32x16_bf16 v[32:47], v[164:167], v[112:115], v[32:47]
	v_exp_f32_e32 v106, v106
	v_exp_f32_e32 v107, v107
	ds_read_b64_tr_b16 v[112:113], v65 offset:31744
	ds_read_b64_tr_b16 v[114:115], v65 offset:32256
	s_waitcnt lgkmcnt(12)
	v_mfma_f32_32x32x16_bf16 v[16:31], v[164:167], v[116:119], v[16:31]
	v_exp_f32_e32 v108, v108
	v_exp_f32_e32 v109, v109
	ds_read_b64_tr_b16 v[116:117], v65 offset:35840
	ds_read_b64_tr_b16 v[118:119], v65 offset:36352
	v_mfma_f32_32x32x16_bf16 v[0:15], v[164:167], v[120:123], v[0:15]
	v_exp_f32_e32 v110, v110
	v_exp_f32_e32 v111, v111
	ds_read_b64_tr_b16 v[120:121], v65 offset:39936
	ds_read_b64_tr_b16 v[122:123], v65 offset:40448
	s_lshl_b32 s24, s27, 1
	s_add_i32 s24, s24, s21
	s_addk_i32 s24, 0x2000
	s_mov_b32 m0, s24
	s_nop 0
	global_load_lds_dwordx4 v[248:249], off
	s_waitcnt lgkmcnt(14)
	v_mfma_f32_32x32x16_bf16 v[48:63], v[156:159], v[68:71], v[48:63]
	v_exp_f32_e32 v80, v80
	v_exp_f32_e32 v81, v81
	s_waitcnt lgkmcnt(12)
	v_mfma_f32_32x32x16_bf16 v[32:47], v[156:159], v[72:75], v[32:47]
	v_exp_f32_e32 v82, v82
	v_exp_f32_e32 v83, v83
	v_add_u32_e32 v65, s27, v241
	ds_read_b128 v[204:207], v65
	ds_read_b128 v[200:203], v65 offset:512
	s_waitcnt lgkmcnt(12)
	v_mfma_f32_32x32x16_bf16 v[16:31], v[156:159], v[76:79], v[16:31]
	v_exp_f32_e32 v84, v84
	v_exp_f32_e32 v85, v85
	ds_read_b128 v[196:199], v65 offset:2048
	ds_read_b128 v[192:195], v65 offset:2560
	s_waitcnt lgkmcnt(12)
	v_mfma_f32_32x32x16_bf16 v[0:15], v[156:159], v[124:127], v[0:15]
	v_exp_f32_e32 v86, v86
	v_exp_f32_e32 v87, v87
	ds_read_b128 v[188:191], v65 offset:4096
	ds_read_b128 v[184:187], v65 offset:4608
	s_waitcnt lgkmcnt(12)
	v_mfma_f32_32x32x16_bf16 v[48:63], v[148:151], v[128:131], v[48:63]
	v_exp_f32_e32 v88, v88
	v_exp_f32_e32 v89, v89
	ds_read_b128 v[180:183], v65 offset:6144
	ds_read_b128 v[176:179], v65 offset:6656
	s_waitcnt lgkmcnt(12)
	v_mfma_f32_32x32x16_bf16 v[32:47], v[148:151], v[112:115], v[32:47]
	v_exp_f32_e32 v90, v90
	v_exp_f32_e32 v91, v91
	s_waitcnt lgkmcnt(10)
	v_mfma_f32_32x32x16_bf16 v[16:31], v[148:151], v[116:119], v[16:31]
	v_exp_f32_e32 v92, v92
	v_exp_f32_e32 v93, v93
	s_waitcnt lgkmcnt(8)
	v_mfma_f32_32x32x16_bf16 v[0:15], v[148:151], v[120:123], v[0:15]
	v_exp_f32_e32 v94, v94
	v_exp_f32_e32 v95, v95
	s_add_i32 s14, s27, 0x2000
	s_cmpk_lg_i32 s27, 0x4000
	s_waitcnt vmcnt(3) lgkmcnt(0)
	s_barrier
	s_cselect_b32 s28, s14, 0
	s_add_u32 s56, s56, 0xc0000
	s_addc_u32 s57, s57, 0
	s_cmp_ge_i32 s35, s11
	s_mov_b32 s15, s37
	s_cbranch_scc0 .LBB0_304
	s_setprio 0
	s_ashr_i32 s11, s10, 31
	s_add_i32 s14, s35, 1
	s_cmp_lt_i32 s14, s25
	s_cbranch_scc1 .LBB0_315
